# XCD-local seams, start stagger 1.5us/XCD (XCD_SLEEP=48)
# speedup vs baseline: 1.0044x; 1.0044x over previous
.Lxl_stag_loop:
	s_sleep 48
	s_add_i32 s101, s101, -1
	s_cmp_lg_u32 s101, 0
	s_cbranch_scc1 .Lxl_stag_loop
